# weight-conversion tail loops (INPROJ0 idle workgroups, SSDOUT0): L2 warm-up loads for the next item's f32 tile issued behind the current item's loads
# baseline (speedup 1.0000x reference)
.LBB0_1353:
	s_cmpk_gt_i32 s38, 0x27f
	s_mov_b64 s[4:5], -1
	s_cbranch_scc0 .LBB0_1408
	s_cmpk_gt_u32 s38, 0x297
	s_cbranch_scc0 .LBB0_1403
	s_cmpk_gt_u32 s38, 0x2a7
	s_cbranch_scc0 .LBB0_1398
	s_cmpk_gt_u32 s38, 0x3a7
	s_cbranch_scc0 .LBB0_1362
	s_cmpk_gt_u32 s38, 0x7a7
	s_cbranch_scc0 .LBB0_1359
	v_mov_b32_e32 v21, v164
	s_and_b32 s0, s60, 0x3c0
	v_and_b32_e32 v24, 63, v21
	v_bfe_u32 v25, v21, 6, 2
	s_and_b32 s1, s61, 0x7fffffc0
	v_or_b32_e32 v1, s0, v24
	v_or_b32_e32 v0, s1, v25
	v_lshlrev_b32_e32 v16, 2, v1
	v_lshl_add_u64 v[2:3], s[16:17], 0, v[16:17]
	v_or_b32_e32 v16, 4, v0
	v_lshlrev_b64 v[6:7], 12, v[16:17]
	v_or_b32_e32 v16, 8, v0
	v_lshlrev_b64 v[8:9], 12, v[16:17]
	v_or_b32_e32 v16, 12, v0
	v_lshlrev_b64 v[10:11], 12, v[16:17]
	v_or_b32_e32 v16, 16, v0
	v_lshlrev_b64 v[12:13], 12, v[16:17]
	v_or_b32_e32 v16, 20, v0
	v_lshlrev_b64 v[14:15], 12, v[16:17]
	v_or_b32_e32 v16, 24, v0
	v_mov_b32_e32 v1, v17
	v_lshlrev_b64 v[18:19], 12, v[16:17]
	v_or_b32_e32 v16, 28, v0
	v_lshlrev_b64 v[4:5], 12, v[0:1]
	v_lshlrev_b64 v[22:23], 12, v[16:17]
	v_lshl_add_u64 v[4:5], v[2:3], 0, v[4:5]
	v_lshl_add_u64 v[22:23], v[2:3], 0, v[22:23]
	v_or_b32_e32 v16, 32, v0
	v_lshl_add_u64 v[6:7], v[2:3], 0, v[6:7]
	v_lshl_add_u64 v[8:9], v[2:3], 0, v[8:9]
	v_lshl_add_u64 v[10:11], v[2:3], 0, v[10:11]
	v_lshl_add_u64 v[12:13], v[2:3], 0, v[12:13]
	v_lshl_add_u64 v[14:15], v[2:3], 0, v[14:15]
	v_lshl_add_u64 v[18:19], v[2:3], 0, v[18:19]
	global_load_dword v26, v[4:5], off
	global_load_dword v27, v[6:7], off
	global_load_dword v28, v[8:9], off
	global_load_dword v29, v[10:11], off
	global_load_dword v30, v[12:13], off
	global_load_dword v31, v[14:15], off
	global_load_dword v32, v[18:19], off
	s_nop 0
	global_load_dword v22, v[22:23], off
	v_lshlrev_b64 v[4:5], 12, v[16:17]
	v_or_b32_e32 v16, 36, v0
	v_lshlrev_b64 v[6:7], 12, v[16:17]
	v_or_b32_e32 v16, 40, v0
	v_lshlrev_b64 v[8:9], 12, v[16:17]
	v_or_b32_e32 v16, 44, v0
	v_lshlrev_b64 v[10:11], 12, v[16:17]
	v_or_b32_e32 v16, 48, v0
	v_lshlrev_b64 v[12:13], 12, v[16:17]
	v_or_b32_e32 v16, 52, v0
	v_lshlrev_b64 v[14:15], 12, v[16:17]
	v_or_b32_e32 v16, 56, v0
	v_lshlrev_b64 v[18:19], 12, v[16:17]
	v_or_b32_e32 v16, 60, v0
	v_lshlrev_b64 v[0:1], 12, v[16:17]
	v_lshl_add_u64 v[4:5], v[2:3], 0, v[4:5]
	v_lshl_add_u64 v[6:7], v[2:3], 0, v[6:7]
	v_lshl_add_u64 v[8:9], v[2:3], 0, v[8:9]
	v_lshl_add_u64 v[0:1], v[2:3], 0, v[0:1]
	v_lshl_add_u64 v[10:11], v[2:3], 0, v[10:11]
	v_lshl_add_u64 v[12:13], v[2:3], 0, v[12:13]
	v_lshl_add_u64 v[14:15], v[2:3], 0, v[14:15]
	v_lshl_add_u64 v[18:19], v[2:3], 0, v[18:19]
	global_load_dword v2, v[4:5], off
	global_load_dword v3, v[6:7], off
	s_nop 0
	global_load_dword v4, v[8:9], off
	global_load_dword v5, v[10:11], off
	global_load_dword v6, v[12:13], off
	global_load_dword v7, v[14:15], off
	s_nop 0
	global_load_dword v8, v[18:19], off
	s_nop 0
	global_load_dword v0, v[0:1], off
	s_add_i32 s98, s38, 0x1a0
	s_cmpk_lt_i32 s98, 0xba8
	s_cselect_b32 s98, s98, s38
	s_cmpk_gt_u32 s98, 0x7a7
	s_cbranch_scc1 .LpfC_ff2
	s_add_i32 s98, s98, 0xfffffc58
	s_lshr_b32 s99, s98, 6
	s_and_b32 s98, s98, 63
	s_lshl_b32 s99, s99, 20
	s_lshl_b32 s98, s98, 8
	s_add_i32 s98, s98, s99
	s_add_u32 s100, s24, s98
	s_addc_u32 s101, s25, 0
	s_mov_b32 s99, 14
	s_branch .LpfC_go
.LpfC_ff2:
	s_add_i32 s98, s98, 0xfffff858
	s_lshr_b32 s99, s98, 4
	s_and_b32 s98, s98, 15
	s_lshl_b32 s99, s99, 18
	s_lshl_b32 s98, s98, 8
	s_add_i32 s98, s98, s99
	s_add_u32 s100, s16, s98
	s_addc_u32 s101, s17, 0
	s_mov_b32 s99, 12
.LpfC_go:
	v_bfe_u32 v222, v164, 6, 2
	v_bfe_u32 v223, v164, 4, 2
	v_lshl_add_u32 v222, v222, 4, v223
	v_lshlrev_b32_e32 v222, s99, v222
	v_and_b32_e32 v223, 15, v164
	v_lshl_add_u32 v222, v223, 4, v222
	s_lshl_b32 s98, 4, s99
	global_load_dwordx4 v[224:227], v222, s[100:101]
	s_add_u32 s100, s100, s98
	s_addc_u32 s101, s101, 0
	global_load_dwordx4 v[228:231], v222, s[100:101]
	s_add_u32 s100, s100, s98
	s_addc_u32 s101, s101, 0
	global_load_dwordx4 v[232:235], v222, s[100:101]
	s_add_u32 s100, s100, s98
	s_addc_u32 s101, s101, 0
	global_load_dwordx4 v[236:239], v222, s[100:101]
	v_lshlrev_b32_e32 v1, 3, v21
	v_mul_u32_u24_e32 v9, 0x104, v25
	v_lshlrev_b32_e32 v10, 2, v24
	v_and_b32_e32 v1, 56, v1
	v_add3_u32 v9, s23, v9, v10
	v_mul_u32_u24_e32 v10, 0x41, v1
	v_bfe_u32 v21, v21, 3, 5
	v_lshlrev_b32_e32 v16, 1, v1
	v_lshlrev_b32_e32 v1, 2, v21
	s_lshl_b32 s1, s1, 1
	s_add_u32 s4, s39, s1
	s_addc_u32 s5, s45, 0
	v_lshl_add_u64 v[24:25], s[4:5], 0, v[16:17]
	s_mov_b64 s[4:5], 0
	s_waitcnt vmcnt(19)
	ds_write_b32 v9, v26
	s_waitcnt vmcnt(18)
	ds_write_b32 v9, v27 offset:1040
	s_waitcnt vmcnt(17)
	ds_write_b32 v9, v28 offset:2080
	s_waitcnt vmcnt(16)
	ds_write_b32 v9, v29 offset:3120
	s_waitcnt vmcnt(15)
	ds_write_b32 v9, v30 offset:4160
	s_waitcnt vmcnt(14)
	ds_write_b32 v9, v31 offset:5200
	s_waitcnt vmcnt(13)
	ds_write_b32 v9, v32 offset:6240
	s_waitcnt vmcnt(12)
	ds_write_b32 v9, v22 offset:7280
	s_waitcnt vmcnt(11)
	ds_write_b32 v9, v2 offset:8320
	s_waitcnt vmcnt(10)
	ds_write_b32 v9, v3 offset:9360
	s_waitcnt vmcnt(9)
	ds_write_b32 v9, v4 offset:10400
	s_waitcnt vmcnt(8)
	ds_write_b32 v9, v5 offset:11440
	s_waitcnt vmcnt(7)
	ds_write_b32 v9, v6 offset:12480
	s_waitcnt vmcnt(6)
	ds_write_b32 v9, v7 offset:13520
	s_waitcnt vmcnt(5)
	ds_write_b32 v9, v8 offset:14560
	s_waitcnt vmcnt(4)
	ds_write_b32 v9, v0 offset:15600
	v_lshlrev_b32_e32 v0, 2, v10
	v_add3_u32 v2, s23, v0, v1
	s_waitcnt lgkmcnt(0)
	s_barrier
	ds_read2_b32 v[4:5], v2 offset1:32
	v_add3_u32 v0, s23, v1, v0
	ds_read2_b32 v[6:7], v0 offset0:65 offset1:97
	ds_read2_b32 v[8:9], v2 offset0:130 offset1:162
	ds_read2_b32 v[10:11], v2 offset0:195 offset1:227
	v_add_u32_e32 v0, 0x400, v2
	ds_read2_b32 v[12:13], v0 offset0:4 offset1:36
	ds_read2_b32 v[14:15], v0 offset0:69 offset1:101
	ds_read2_b32 v[18:19], v0 offset0:134 offset1:166
	ds_read2_b32 v[22:23], v0 offset0:199 offset1:231
	s_waitcnt lgkmcnt(6)
	v_cvt_pk_bf16_f32 v0, v4, v6
	v_or_b32_e32 v4, s0, v21
	v_lshlrev_b32_e32 v16, 13, v4
	s_waitcnt lgkmcnt(4)
	v_cvt_pk_bf16_f32 v1, v8, v10
	s_waitcnt lgkmcnt(2)
	v_cvt_pk_bf16_f32 v2, v12, v14
	s_waitcnt lgkmcnt(0)
	v_cvt_pk_bf16_f32 v3, v18, v22
	v_lshl_add_u64 v[26:27], v[24:25], 0, v[16:17]
	v_or_b32_e32 v16, 0x40000, v16
	global_store_dwordx4 v[26:27], v[0:3], off
	s_nop 1
	v_cvt_pk_bf16_f32 v0, v5, v7
	v_cvt_pk_bf16_f32 v1, v9, v11
	v_cvt_pk_bf16_f32 v2, v13, v15
	v_cvt_pk_bf16_f32 v3, v19, v23
	v_lshl_add_u64 v[4:5], v[24:25], 0, v[16:17]
	global_store_dwordx4 v[4:5], v[0:3], off
	s_barrier
.LBB0_1359:
	s_andn2_b64 vcc, exec, s[4:5]
	s_cbranch_vccnz .LBB0_1361
	s_add_i32 s0, s38, 0xfffffc58
	s_and_b32 s6, s0, 0xffffffc0
	v_mov_b32_e32 v21, v164
	s_add_i32 s0, s60, 0x10000
	s_and_b32 s0, s0, 0xfc0
	v_and_b32_e32 v24, 63, v21
	v_bfe_u32 v25, v21, 6, 2
	v_or_b32_e32 v1, s0, v24
	v_or_b32_e32 v0, s6, v25
	v_lshlrev_b32_e32 v16, 2, v1
	v_lshl_add_u64 v[2:3], s[24:25], 0, v[16:17]
	v_or_b32_e32 v16, 4, v0
	v_lshlrev_b64 v[6:7], 14, v[16:17]
	v_or_b32_e32 v16, 8, v0
	v_lshlrev_b64 v[8:9], 14, v[16:17]
	v_or_b32_e32 v16, 12, v0
	v_lshlrev_b64 v[10:11], 14, v[16:17]
	v_or_b32_e32 v16, 16, v0
	v_lshlrev_b64 v[12:13], 14, v[16:17]
	v_or_b32_e32 v16, 20, v0
	v_lshlrev_b64 v[14:15], 14, v[16:17]
	v_or_b32_e32 v16, 24, v0
	v_mov_b32_e32 v1, v17
	v_lshlrev_b64 v[18:19], 14, v[16:17]
	v_or_b32_e32 v16, 28, v0
	v_lshlrev_b64 v[4:5], 14, v[0:1]
	v_lshlrev_b64 v[22:23], 14, v[16:17]
	v_lshl_add_u64 v[4:5], v[2:3], 0, v[4:5]
	v_lshl_add_u64 v[22:23], v[2:3], 0, v[22:23]
	v_or_b32_e32 v16, 32, v0
	v_lshl_add_u64 v[6:7], v[2:3], 0, v[6:7]
	v_lshl_add_u64 v[8:9], v[2:3], 0, v[8:9]
	v_lshl_add_u64 v[10:11], v[2:3], 0, v[10:11]
	v_lshl_add_u64 v[12:13], v[2:3], 0, v[12:13]
	v_lshl_add_u64 v[14:15], v[2:3], 0, v[14:15]
	v_lshl_add_u64 v[18:19], v[2:3], 0, v[18:19]
	global_load_dword v26, v[4:5], off
	global_load_dword v27, v[6:7], off
	global_load_dword v28, v[8:9], off
	global_load_dword v29, v[10:11], off
	global_load_dword v30, v[12:13], off
	global_load_dword v31, v[14:15], off
	global_load_dword v32, v[18:19], off
	s_nop 0
	global_load_dword v22, v[22:23], off
	v_lshlrev_b64 v[4:5], 14, v[16:17]
	v_or_b32_e32 v16, 36, v0
	v_lshlrev_b64 v[6:7], 14, v[16:17]
	v_or_b32_e32 v16, 40, v0
	v_lshlrev_b64 v[8:9], 14, v[16:17]
	v_or_b32_e32 v16, 44, v0
	v_lshlrev_b64 v[10:11], 14, v[16:17]
	v_or_b32_e32 v16, 48, v0
	v_lshlrev_b64 v[12:13], 14, v[16:17]
	v_or_b32_e32 v16, 52, v0
	v_lshlrev_b64 v[14:15], 14, v[16:17]
	v_or_b32_e32 v16, 56, v0
	v_lshlrev_b64 v[18:19], 14, v[16:17]
	v_or_b32_e32 v16, 60, v0
	v_lshlrev_b64 v[0:1], 14, v[16:17]
	v_lshl_add_u64 v[4:5], v[2:3], 0, v[4:5]
	v_lshl_add_u64 v[6:7], v[2:3], 0, v[6:7]
	v_lshl_add_u64 v[8:9], v[2:3], 0, v[8:9]
	v_lshl_add_u64 v[0:1], v[2:3], 0, v[0:1]
	v_lshl_add_u64 v[10:11], v[2:3], 0, v[10:11]
	v_lshl_add_u64 v[12:13], v[2:3], 0, v[12:13]
	v_lshl_add_u64 v[14:15], v[2:3], 0, v[14:15]
	v_lshl_add_u64 v[18:19], v[2:3], 0, v[18:19]
	global_load_dword v2, v[4:5], off
	global_load_dword v3, v[6:7], off
	s_nop 0
	global_load_dword v4, v[8:9], off
	global_load_dword v5, v[10:11], off
	global_load_dword v6, v[12:13], off
	global_load_dword v7, v[14:15], off
	s_nop 0
	global_load_dword v8, v[18:19], off
	s_nop 0
	global_load_dword v0, v[0:1], off
	s_add_i32 s98, s38, 0x1a0
	s_cmpk_lt_i32 s98, 0xba8
	s_cselect_b32 s98, s98, s38
	s_cmpk_gt_u32 s98, 0x7a7
	s_cbranch_scc1 .LpfD_ff2
	s_add_i32 s98, s98, 0xfffffc58
	s_lshr_b32 s99, s98, 6
	s_and_b32 s98, s98, 63
	s_lshl_b32 s99, s99, 20
	s_lshl_b32 s98, s98, 8
	s_add_i32 s98, s98, s99
	s_add_u32 s100, s24, s98
	s_addc_u32 s101, s25, 0
	s_mov_b32 s99, 14
	s_branch .LpfD_go

.LpfD_go:
	v_bfe_u32 v222, v164, 6, 2
	v_bfe_u32 v223, v164, 4, 2
	v_lshl_add_u32 v222, v222, 4, v223
	v_lshlrev_b32_e32 v222, s99, v222
	v_and_b32_e32 v223, 15, v164
	v_lshl_add_u32 v222, v223, 4, v222
	s_lshl_b32 s98, 4, s99
	global_load_dwordx4 v[224:227], v222, s[100:101]
	s_add_u32 s100, s100, s98
	s_addc_u32 s101, s101, 0
	global_load_dwordx4 v[228:231], v222, s[100:101]
	s_add_u32 s100, s100, s98
	s_addc_u32 s101, s101, 0
	global_load_dwordx4 v[232:235], v222, s[100:101]
	s_add_u32 s100, s100, s98
	s_addc_u32 s101, s101, 0
	global_load_dwordx4 v[236:239], v222, s[100:101]
	v_lshlrev_b32_e32 v1, 3, v21
	v_mul_u32_u24_e32 v9, 0x104, v25
	v_lshlrev_b32_e32 v10, 2, v24
	v_and_b32_e32 v1, 56, v1
	v_add3_u32 v9, s23, v9, v10
	v_bfe_u32 v21, v21, 3, 5
	v_lshlrev_b32_e32 v16, 1, v1
	s_lshl_b64 s[4:5], s[6:7], 1
	s_add_u32 s4, s46, s4
	s_addc_u32 s5, s47, s5
	v_lshl_add_u64 v[24:25], s[4:5], 0, v[16:17]
	s_waitcnt vmcnt(19)
	ds_write_b32 v9, v26
	s_waitcnt vmcnt(18)
	ds_write_b32 v9, v27 offset:1040
	s_waitcnt vmcnt(17)
	ds_write_b32 v9, v28 offset:2080
	s_waitcnt vmcnt(16)
	ds_write_b32 v9, v29 offset:3120
	s_waitcnt vmcnt(15)
	ds_write_b32 v9, v30 offset:4160
	s_waitcnt vmcnt(14)
	ds_write_b32 v9, v31 offset:5200
	s_waitcnt vmcnt(13)
	ds_write_b32 v9, v32 offset:6240
	s_waitcnt vmcnt(12)
	ds_write_b32 v9, v22 offset:7280
	s_waitcnt vmcnt(11)
	ds_write_b32 v9, v2 offset:8320
	s_waitcnt vmcnt(10)
	ds_write_b32 v9, v3 offset:9360
	s_waitcnt vmcnt(9)
	ds_write_b32 v9, v4 offset:10400
	s_waitcnt vmcnt(8)
	ds_write_b32 v9, v5 offset:11440
	s_waitcnt vmcnt(7)
	ds_write_b32 v9, v6 offset:12480
	s_waitcnt vmcnt(6)
	ds_write_b32 v9, v7 offset:13520
	s_waitcnt vmcnt(5)
	ds_write_b32 v9, v8 offset:14560
	s_waitcnt vmcnt(4)
	ds_write_b32 v9, v0 offset:15600
	v_mul_u32_u24_e32 v0, 0x41, v1
	v_lshlrev_b32_e32 v0, 2, v0
	v_lshlrev_b32_e32 v1, 2, v21
	v_add3_u32 v2, s23, v0, v1
	s_waitcnt lgkmcnt(0)
	s_barrier
	ds_read2_b32 v[4:5], v2 offset1:32
	v_add3_u32 v0, s23, v1, v0
	ds_read2_b32 v[6:7], v0 offset0:65 offset1:97
	ds_read2_b32 v[8:9], v2 offset0:130 offset1:162
	ds_read2_b32 v[10:11], v2 offset0:195 offset1:227
	v_add_u32_e32 v0, 0x400, v2
	ds_read2_b32 v[12:13], v0 offset0:4 offset1:36
	ds_read2_b32 v[14:15], v0 offset0:69 offset1:101
	ds_read2_b32 v[18:19], v0 offset0:134 offset1:166
	ds_read2_b32 v[22:23], v0 offset0:199 offset1:231
	s_waitcnt lgkmcnt(6)
	v_cvt_pk_bf16_f32 v0, v4, v6
	v_or_b32_e32 v4, s0, v21
	v_lshlrev_b32_e32 v16, 11, v4
	s_waitcnt lgkmcnt(4)
	v_cvt_pk_bf16_f32 v1, v8, v10
	s_waitcnt lgkmcnt(2)
	v_cvt_pk_bf16_f32 v2, v12, v14
	s_waitcnt lgkmcnt(0)
	v_cvt_pk_bf16_f32 v3, v18, v22
	v_lshl_add_u64 v[26:27], v[24:25], 0, v[16:17]
	v_or_b32_e32 v16, 0x10000, v16
	global_store_dwordx4 v[26:27], v[0:3], off
	s_nop 1
	v_cvt_pk_bf16_f32 v0, v5, v7
	v_cvt_pk_bf16_f32 v1, v9, v11
	v_cvt_pk_bf16_f32 v2, v13, v15
	v_cvt_pk_bf16_f32 v3, v19, v23
	v_lshl_add_u64 v[4:5], v[24:25], 0, v[16:17]
	global_store_dwordx4 v[4:5], v[0:3], off
	s_barrier
